# v082 + the full vmcnt(0) drain at the start of each GEMM unit (in the accumulator-zeroing block) removed: epilogue stores retire under the next unit's decode / zeroing / first load block, the loop's c
# baseline (speedup 1.0000x reference)
; #define PG8_BAR __builtin_amdgcn_s_barrier()
; template <class Epi, class Sched>
; __device__ __forceinline__ void gemm_phase(LAS unsigned char* lds, const int tid, const Gemm g, const Sched& S, const Epi& E) {
;     ...
; #pragma unroll
;         for (int a = 0; a < 2; ++a)
; #pragma unroll
;             for (int b = 0; b < 2; ++b)
; #pragma unroll
;                 for (int m = 0; m < 4; ++m)
; #pragma unroll
;                     for (int n = 0; n < 2; ++n) acc[a][b][m][n] = (f32x4){0.f, 0.f, 0.f, 0.f};
;         cur = nxt; cA = nA; cB = nB; ++ui;
;         if (wr == 1) PG8_BAR;
.LBB0_318:
	s_add_u32 s31, s72, 0x100
	v_mov_b32_e32 v2, 0
	s_addc_u32 s93, s73, 0
	s_mov_b32 s29, -2
	v_mov_b32_e32 v3, v2
	v_mov_b32_e32 v4, v2
	v_mov_b32_e32 v5, v2
	v_mov_b32_e32 v6, v2
	v_mov_b32_e32 v7, v2
	v_mov_b32_e32 v8, v2
	v_mov_b32_e32 v9, v2
	v_mov_b32_e32 v18, v2
	v_mov_b32_e32 v19, v2
	v_mov_b32_e32 v20, v2
	v_mov_b32_e32 v21, v2
	v_mov_b32_e32 v22, v2
	v_mov_b32_e32 v23, v2
	v_mov_b32_e32 v24, v2
	v_mov_b32_e32 v25, v2
	v_mov_b32_e32 v34, v2
	v_mov_b32_e32 v35, v2
	v_mov_b32_e32 v36, v2
	v_mov_b32_e32 v37, v2
	v_mov_b32_e32 v38, v2
	v_mov_b32_e32 v39, v2
	v_mov_b32_e32 v40, v2
	v_mov_b32_e32 v41, v2
	v_mov_b32_e32 v50, v2
	v_mov_b32_e32 v51, v2
	v_mov_b32_e32 v52, v2
	v_mov_b32_e32 v53, v2
	v_mov_b32_e32 v54, v2
	v_mov_b32_e32 v55, v2
	v_mov_b32_e32 v56, v2
	v_mov_b32_e32 v57, v2
	v_mov_b32_e32 v10, v2
	v_mov_b32_e32 v11, v2
	v_mov_b32_e32 v12, v2
	v_mov_b32_e32 v13, v2
	v_mov_b32_e32 v14, v2
	v_mov_b32_e32 v15, v2
	v_mov_b32_e32 v16, v2
	v_mov_b32_e32 v17, v2
	v_mov_b32_e32 v26, v2
	v_mov_b32_e32 v27, v2
	v_mov_b32_e32 v28, v2
	v_mov_b32_e32 v29, v2
	v_mov_b32_e32 v30, v2
	v_mov_b32_e32 v31, v2
	v_mov_b32_e32 v32, v2
	v_mov_b32_e32 v33, v2
	v_mov_b32_e32 v42, v2
	v_mov_b32_e32 v43, v2
	v_mov_b32_e32 v44, v2
	v_mov_b32_e32 v45, v2
	v_mov_b32_e32 v46, v2
	v_mov_b32_e32 v47, v2
	v_mov_b32_e32 v48, v2
	v_mov_b32_e32 v49, v2
	v_mov_b32_e32 v58, v2
	v_mov_b32_e32 v59, v2
	v_mov_b32_e32 v60, v2
	v_mov_b32_e32 v61, v2
	v_mov_b32_e32 v62, v2
	v_mov_b32_e32 v63, v2
	v_mov_b32_e32 v64, v2
	v_mov_b32_e32 v65, v2
	v_mov_b32_e32 v66, v2
	v_mov_b32_e32 v67, v2
	v_mov_b32_e32 v68, v2
	v_mov_b32_e32 v69, v2
	v_mov_b32_e32 v70, v2
	v_mov_b32_e32 v71, v2
	v_mov_b32_e32 v72, v2
	v_mov_b32_e32 v73, v2
	v_mov_b32_e32 v82, v2
	v_mov_b32_e32 v83, v2
	v_mov_b32_e32 v84, v2
	v_mov_b32_e32 v85, v2
	v_mov_b32_e32 v86, v2
	v_mov_b32_e32 v87, v2
	v_mov_b32_e32 v88, v2
	v_mov_b32_e32 v89, v2
	v_mov_b32_e32 v98, v2
	v_mov_b32_e32 v99, v2
	v_mov_b32_e32 v100, v2
	v_mov_b32_e32 v101, v2
	v_mov_b32_e32 v102, v2
	v_mov_b32_e32 v103, v2
	v_mov_b32_e32 v104, v2
	v_mov_b32_e32 v105, v2
	v_mov_b32_e32 v114, v2
	v_mov_b32_e32 v115, v2
	v_mov_b32_e32 v116, v2
	v_mov_b32_e32 v117, v2
	v_mov_b32_e32 v118, v2
	v_mov_b32_e32 v119, v2
	v_mov_b32_e32 v120, v2
	v_mov_b32_e32 v121, v2
	v_mov_b32_e32 v74, v2
	v_mov_b32_e32 v75, v2
	v_mov_b32_e32 v76, v2
	v_mov_b32_e32 v77, v2
	v_mov_b32_e32 v78, v2
	v_mov_b32_e32 v79, v2
	v_mov_b32_e32 v80, v2
	v_mov_b32_e32 v81, v2
	v_mov_b32_e32 v90, v2
	v_mov_b32_e32 v91, v2
	v_mov_b32_e32 v92, v2
	v_mov_b32_e32 v93, v2
	v_mov_b32_e32 v94, v2
	v_mov_b32_e32 v95, v2
	v_mov_b32_e32 v96, v2
	v_mov_b32_e32 v97, v2
	v_mov_b32_e32 v106, v2
	v_mov_b32_e32 v107, v2
	v_mov_b32_e32 v108, v2
	v_mov_b32_e32 v109, v2
	v_mov_b32_e32 v110, v2
	v_mov_b32_e32 v111, v2
	v_mov_b32_e32 v112, v2
	v_mov_b32_e32 v113, v2
	v_mov_b32_e32 v122, v2
	v_mov_b32_e32 v123, v2
	v_mov_b32_e32 v124, v2
	v_mov_b32_e32 v125, v2
	v_mov_b32_e32 v126, v2
	v_mov_b32_e32 v127, v2
	v_mov_b32_e32 v128, v2
	v_mov_b32_e32 v129, v2
	v_add_u32_e32 v201, 0x80, v0
	v_add_u32_e32 v247, 0x80, v158
	v_add_u32_e32 v249, 0x80, v154
	v_add_u32_e32 v251, 0x80, v156

;     __device__ bool next(int i, Unit& u) const { if (!b.next(i / 3, u)) return false; u.pz = i % 3; return true; }
; #define PG8_BAR __builtin_amdgcn_s_barrier()
; template <class Epi, class Sched>
; __device__ __forceinline__ void gemm_phase(LAS unsigned char* lds, const int tid, const Gemm g, const Sched& S, const Epi& E) {
;     ...
;         const bool has_next = S.next(ui + 1, nxt);
;         const gchar* nA = has_next ? (const gchar*)g.A + (size_t)nxt.pm * tstep + (size_t)nxt.pz * g.zA : cA;
;         const gchar* nB = has_next ? (const gchar*)g.Bt + (size_t)nxt.pn * tstep + (size_t)nxt.pz * g.zB : cB;
;     ...
; #pragma unroll
;         for (int a = 0; a < 2; ++a)
; #pragma unroll
;             for (int b = 0; b < 2; ++b)
; #pragma unroll
;                 for (int m = 0; m < 4; ++m)
; #pragma unroll
;                     for (int n = 0; n < 2; ++n) acc[a][b][m][n] = (f32x4){0.f, 0.f, 0.f, 0.f};
;         cur = nxt; cA = nA; cB = nB; ++ui;
;         if (wr == 1) PG8_BAR;
.LBB0_368:
	s_ashr_i32 s11, s10, 31
	s_lshl_b64 s[46:47], s[10:11], 19
	s_add_u32 s60, s86, s46
	s_addc_u32 s61, s87, s47
	s_and_b64 s[46:47], s[2:3], exec
	s_cselect_b32 s11, s61, s21
	s_cselect_b32 s12, s60, s20
	s_ashr_i32 s9, s8, 31
	s_lshl_b64 s[46:47], s[8:9], 19
	s_add_u32 s62, s58, s46
	s_addc_u32 s63, s59, s47
	s_and_b64 s[46:47], s[2:3], exec
	s_cselect_b32 s9, s63, s17
	s_cselect_b32 s15, s62, s16
	s_add_u32 s23, s16, 0x100
	s_addc_u32 s24, s17, 0
	s_add_u32 s16, s20, 0x40080
	v_mov_b32_e32 v2, 0
	s_addc_u32 s17, s21, 0
	s_mov_b32 s31, -2
	v_mov_b32_e32 v3, v2
	v_mov_b32_e32 v4, v2
	v_mov_b32_e32 v5, v2
	v_mov_b32_e32 v10, v2
	v_mov_b32_e32 v11, v2
	v_mov_b32_e32 v12, v2
	v_mov_b32_e32 v13, v2
	v_mov_b32_e32 v18, v2
	v_mov_b32_e32 v19, v2
	v_mov_b32_e32 v20, v2
	v_mov_b32_e32 v21, v2
	v_mov_b32_e32 v26, v2
	v_mov_b32_e32 v27, v2
	v_mov_b32_e32 v28, v2
	v_mov_b32_e32 v29, v2
	v_mov_b32_e32 v34, v2
	v_mov_b32_e32 v35, v2
	v_mov_b32_e32 v36, v2
	v_mov_b32_e32 v37, v2
	v_mov_b32_e32 v42, v2
	v_mov_b32_e32 v43, v2
	v_mov_b32_e32 v44, v2
	v_mov_b32_e32 v45, v2
	v_mov_b32_e32 v50, v2
	v_mov_b32_e32 v51, v2
	v_mov_b32_e32 v52, v2
	v_mov_b32_e32 v53, v2
	v_mov_b32_e32 v58, v2
	v_mov_b32_e32 v59, v2
	v_mov_b32_e32 v60, v2
	v_mov_b32_e32 v61, v2
	v_mov_b32_e32 v6, v2
	v_mov_b32_e32 v7, v2
	v_mov_b32_e32 v8, v2
	v_mov_b32_e32 v9, v2
	v_mov_b32_e32 v14, v2
	v_mov_b32_e32 v15, v2
	v_mov_b32_e32 v16, v2
	v_mov_b32_e32 v17, v2
	v_mov_b32_e32 v22, v2
	v_mov_b32_e32 v23, v2
	v_mov_b32_e32 v24, v2
	v_mov_b32_e32 v25, v2
	v_mov_b32_e32 v30, v2
	v_mov_b32_e32 v31, v2
	v_mov_b32_e32 v32, v2
	v_mov_b32_e32 v33, v2
	v_mov_b32_e32 v38, v2
	v_mov_b32_e32 v39, v2
	v_mov_b32_e32 v40, v2
	v_mov_b32_e32 v41, v2
	v_mov_b32_e32 v46, v2
	v_mov_b32_e32 v47, v2
	v_mov_b32_e32 v48, v2
	v_mov_b32_e32 v49, v2
	v_mov_b32_e32 v54, v2
	v_mov_b32_e32 v55, v2
	v_mov_b32_e32 v56, v2
	v_mov_b32_e32 v57, v2
	v_mov_b32_e32 v62, v2
	v_mov_b32_e32 v63, v2
	v_mov_b32_e32 v64, v2
	v_mov_b32_e32 v65, v2
	v_mov_b32_e32 v66, v2
	v_mov_b32_e32 v67, v2
	v_mov_b32_e32 v68, v2
	v_mov_b32_e32 v69, v2
	v_mov_b32_e32 v74, v2
	v_mov_b32_e32 v75, v2
	v_mov_b32_e32 v76, v2
	v_mov_b32_e32 v77, v2
	v_mov_b32_e32 v82, v2
	v_mov_b32_e32 v83, v2
	v_mov_b32_e32 v84, v2
	v_mov_b32_e32 v85, v2
	v_mov_b32_e32 v90, v2
	v_mov_b32_e32 v91, v2
	v_mov_b32_e32 v92, v2
	v_mov_b32_e32 v93, v2
	v_mov_b32_e32 v98, v2
	v_mov_b32_e32 v99, v2
	v_mov_b32_e32 v100, v2
	v_mov_b32_e32 v101, v2
	v_mov_b32_e32 v106, v2
	v_mov_b32_e32 v107, v2
	v_mov_b32_e32 v108, v2
	v_mov_b32_e32 v109, v2
	v_mov_b32_e32 v114, v2
	v_mov_b32_e32 v115, v2
	v_mov_b32_e32 v116, v2
	v_mov_b32_e32 v117, v2
	v_mov_b32_e32 v122, v2
	v_mov_b32_e32 v123, v2
	v_mov_b32_e32 v124, v2
	v_mov_b32_e32 v125, v2
	v_mov_b32_e32 v70, v2
	v_mov_b32_e32 v71, v2
	v_mov_b32_e32 v72, v2
	v_mov_b32_e32 v73, v2
	v_mov_b32_e32 v78, v2
	v_mov_b32_e32 v79, v2
	v_mov_b32_e32 v80, v2
	v_mov_b32_e32 v81, v2
	v_mov_b32_e32 v86, v2
	v_mov_b32_e32 v87, v2
	v_mov_b32_e32 v88, v2
	v_mov_b32_e32 v89, v2
	v_mov_b32_e32 v94, v2
	v_mov_b32_e32 v95, v2
	v_mov_b32_e32 v96, v2
	v_mov_b32_e32 v97, v2
	v_mov_b32_e32 v102, v2
	v_mov_b32_e32 v103, v2
	v_mov_b32_e32 v104, v2
	v_mov_b32_e32 v105, v2
	v_mov_b32_e32 v110, v2
	v_mov_b32_e32 v111, v2
	v_mov_b32_e32 v112, v2
	v_mov_b32_e32 v113, v2
	v_mov_b32_e32 v118, v2
	v_mov_b32_e32 v119, v2
	v_mov_b32_e32 v120, v2
	v_mov_b32_e32 v121, v2
	v_mov_b32_e32 v126, v2
	v_mov_b32_e32 v127, v2
	v_mov_b32_e32 v128, v2
	v_mov_b32_e32 v129, v2
	v_add_u32_e32 v141, 0x80, v0
	v_add_u32_e32 v153, 0x80, v130
	v_add_u32_e32 v201, 0x80, v134
	v_add_u32_e32 v225, 0x80, v132

;     __device__ bool next(int i, Unit& u) const { if (!b.next(i / 3, u)) return false; u.pz = i % 3; return true; }
; #define PG8_BAR __builtin_amdgcn_s_barrier()
; template <class Epi, class Sched>
; __device__ __forceinline__ void gemm_phase(LAS unsigned char* lds, const int tid, const Gemm g, const Sched& S, const Epi& E) {
;     ...
;         const bool has_next = S.next(ui + 1, nxt);
;         const gchar* nA = has_next ? (const gchar*)g.A + (size_t)nxt.pm * tstep + (size_t)nxt.pz * g.zA : cA;
;         const gchar* nB = has_next ? (const gchar*)g.Bt + (size_t)nxt.pn * tstep + (size_t)nxt.pz * g.zB : cB;
;     ...
; #pragma unroll
;         for (int a = 0; a < 2; ++a)
; #pragma unroll
;             for (int b = 0; b < 2; ++b)
; #pragma unroll
;                 for (int m = 0; m < 4; ++m)
; #pragma unroll
;                     for (int n = 0; n < 2; ++n) acc[a][b][m][n] = (f32x4){0.f, 0.f, 0.f, 0.f};
;         cur = nxt; cA = nA; cB = nB; ++ui;
;         if (wr == 1) PG8_BAR;
.LBB0_396:
	s_ashr_i32 s57, s56, 31
	s_lshl_b64 s[50:51], s[56:57], 19
	s_add_u32 s58, s64, s50
	s_addc_u32 s59, s41, s51
	s_and_b64 s[50:51], s[6:7], exec
	s_cselect_b32 s1, s59, s93
	s_cselect_b32 s31, s58, s92
	s_ashr_i32 s17, s16, 31
	s_lshl_b64 s[50:51], s[16:17], 19
	s_add_u32 s60, s23, s50
	s_addc_u32 s61, s24, s51
	s_and_b64 s[50:51], s[6:7], exec
	s_cselect_b32 s17, s61, s21
	s_cselect_b32 s50, s60, s20
	s_add_u32 s51, s20, 0x100
	s_addc_u32 s52, s21, 0
	s_add_u32 s92, s92, 0x40080
	v_mov_b32_e32 v2, 0
	s_addc_u32 s93, s93, 0
	s_mov_b32 s53, -2
	s_waitcnt lgkmcnt(0)
	v_mov_b32_e32 v3, v2
	v_mov_b32_e32 v4, v2
	v_mov_b32_e32 v5, v2
	v_mov_b32_e32 v6, v2
	v_mov_b32_e32 v7, v2
	v_mov_b32_e32 v8, v2
	v_mov_b32_e32 v9, v2
	v_mov_b32_e32 v18, v2
	v_mov_b32_e32 v19, v2
	v_mov_b32_e32 v20, v2
	v_mov_b32_e32 v21, v2
	v_mov_b32_e32 v22, v2
	v_mov_b32_e32 v23, v2
	v_mov_b32_e32 v24, v2
	v_mov_b32_e32 v25, v2
	v_mov_b32_e32 v34, v2
	v_mov_b32_e32 v35, v2
	v_mov_b32_e32 v36, v2
	v_mov_b32_e32 v37, v2
	v_mov_b32_e32 v38, v2
	v_mov_b32_e32 v39, v2
	v_mov_b32_e32 v40, v2
	v_mov_b32_e32 v41, v2
	v_mov_b32_e32 v50, v2
	v_mov_b32_e32 v51, v2
	v_mov_b32_e32 v52, v2
	v_mov_b32_e32 v53, v2
	v_mov_b32_e32 v54, v2
	v_mov_b32_e32 v55, v2
	v_mov_b32_e32 v56, v2
	v_mov_b32_e32 v57, v2
	v_mov_b32_e32 v10, v2
	v_mov_b32_e32 v11, v2
	v_mov_b32_e32 v12, v2
	v_mov_b32_e32 v13, v2
	v_mov_b32_e32 v14, v2
	v_mov_b32_e32 v15, v2
	v_mov_b32_e32 v16, v2
	v_mov_b32_e32 v17, v2
	v_mov_b32_e32 v26, v2
	v_mov_b32_e32 v27, v2
	v_mov_b32_e32 v28, v2
	v_mov_b32_e32 v29, v2
	v_mov_b32_e32 v30, v2
	v_mov_b32_e32 v31, v2
	v_mov_b32_e32 v32, v2
	v_mov_b32_e32 v33, v2
	v_mov_b32_e32 v42, v2
	v_mov_b32_e32 v43, v2
	v_mov_b32_e32 v44, v2
	v_mov_b32_e32 v45, v2
	v_mov_b32_e32 v46, v2
	v_mov_b32_e32 v47, v2
	v_mov_b32_e32 v48, v2
	v_mov_b32_e32 v49, v2
	v_mov_b32_e32 v58, v2
	v_mov_b32_e32 v59, v2
	v_mov_b32_e32 v60, v2
	v_mov_b32_e32 v61, v2
	v_mov_b32_e32 v62, v2
	v_mov_b32_e32 v63, v2
	v_mov_b32_e32 v64, v2
	v_mov_b32_e32 v65, v2
	v_mov_b32_e32 v66, v2
	v_mov_b32_e32 v67, v2
	v_mov_b32_e32 v68, v2
	v_mov_b32_e32 v69, v2
	v_mov_b32_e32 v70, v2
	v_mov_b32_e32 v71, v2
	v_mov_b32_e32 v72, v2
	v_mov_b32_e32 v73, v2
	v_mov_b32_e32 v82, v2
	v_mov_b32_e32 v83, v2
	v_mov_b32_e32 v84, v2
	v_mov_b32_e32 v85, v2
	v_mov_b32_e32 v86, v2
	v_mov_b32_e32 v87, v2
	v_mov_b32_e32 v88, v2
	v_mov_b32_e32 v89, v2
	v_mov_b32_e32 v98, v2
	v_mov_b32_e32 v99, v2
	v_mov_b32_e32 v100, v2
	v_mov_b32_e32 v101, v2
	v_mov_b32_e32 v102, v2
	v_mov_b32_e32 v103, v2
	v_mov_b32_e32 v104, v2
	v_mov_b32_e32 v105, v2
	v_mov_b32_e32 v114, v2
	v_mov_b32_e32 v115, v2
	v_mov_b32_e32 v116, v2
	v_mov_b32_e32 v117, v2
	v_mov_b32_e32 v118, v2
	v_mov_b32_e32 v119, v2
	v_mov_b32_e32 v120, v2
	v_mov_b32_e32 v121, v2
	v_mov_b32_e32 v74, v2
	v_mov_b32_e32 v75, v2
	v_mov_b32_e32 v76, v2
	v_mov_b32_e32 v77, v2
	v_mov_b32_e32 v78, v2
	v_mov_b32_e32 v79, v2
	v_mov_b32_e32 v80, v2
	v_mov_b32_e32 v81, v2
	v_mov_b32_e32 v90, v2
	v_mov_b32_e32 v91, v2
	v_mov_b32_e32 v92, v2
	v_mov_b32_e32 v93, v2
	v_mov_b32_e32 v94, v2
	v_mov_b32_e32 v95, v2
	v_mov_b32_e32 v96, v2
	v_mov_b32_e32 v97, v2
	v_mov_b32_e32 v106, v2
	v_mov_b32_e32 v107, v2
	v_mov_b32_e32 v108, v2
	v_mov_b32_e32 v109, v2
	v_mov_b32_e32 v110, v2
	v_mov_b32_e32 v111, v2
	v_mov_b32_e32 v112, v2
	v_mov_b32_e32 v113, v2
	v_mov_b32_e32 v122, v2
	v_mov_b32_e32 v123, v2
	v_mov_b32_e32 v124, v2
	v_mov_b32_e32 v125, v2
	v_mov_b32_e32 v126, v2
	v_mov_b32_e32 v127, v2
	v_mov_b32_e32 v128, v2
	v_mov_b32_e32 v129, v2
	v_add_u32_e32 v195, 0x80, v0
	v_add_u32_e32 v201, 0x80, v158
	v_add_u32_e32 v221, 0x80, v154
	v_add_u32_e32 v223, 0x80, v156

; #define PG8_BAR __builtin_amdgcn_s_barrier()
;     __device__ bool next(int i, Unit& u) const { if (!b.next(i / 3, u)) return false; u.pz = i % 3; return true; }
; template <class Epi, class Sched>
; __device__ __forceinline__ void gemm_phase(LAS unsigned char* lds, const int tid, const Gemm g, const Sched& S, const Epi& E) {
;     ...
;         const bool has_next = S.next(ui + 1, nxt);
;         const gchar* nA = has_next ? (const gchar*)g.A + (size_t)nxt.pm * tstep + (size_t)nxt.pz * g.zA : cA;
;         const gchar* nB = has_next ? (const gchar*)g.Bt + (size_t)nxt.pn * tstep + (size_t)nxt.pz * g.zB : cB;
;     ...
; #pragma unroll
;         for (int a = 0; a < 2; ++a)
; #pragma unroll
;             for (int b = 0; b < 2; ++b)
; #pragma unroll
;                 for (int m = 0; m < 4; ++m)
; #pragma unroll
;                     for (int n = 0; n < 2; ++n) acc[a][b][m][n] = (f32x4){0.f, 0.f, 0.f, 0.f};
;         cur = nxt; cA = nA; cB = nB; ++ui;
;         if (wr == 1) PG8_BAR;
.LBB0_443:
	s_ashr_i32 s71, s70, 31
	s_lshl_b64 s[52:53], s[70:71], 18
	s_add_u32 s1, s74, s52
	s_addc_u32 s5, s75, s53
	s_ashr_i32 s63, s62, 31
	s_lshl_b64 s[52:53], s[62:63], 25
	s_add_u32 s56, s1, s52
	s_addc_u32 s57, s5, s53
	s_and_b64 s[52:53], s[2:3], exec
	s_cselect_b32 s1, s57, s21
	s_cselect_b32 s5, s56, s20
	s_ashr_i32 s61, s60, 31
	s_lshl_b64 s[52:53], s[60:61], 18
	s_add_u32 s15, s43, s52
	s_addc_u32 s23, s92, s53
	s_lshl_b64 s[52:53], s[62:63], 20
	s_add_u32 s58, s15, s52
	s_addc_u32 s59, s23, s53
	s_and_b64 s[52:53], s[2:3], exec
	s_cselect_b32 s15, s59, s17
	s_cselect_b32 s23, s58, s16
	s_add_u32 s24, s16, 0x100
	s_addc_u32 s31, s17, 0
	s_add_u32 s16, s20, 0x20080
	v_mov_b32_e32 v2, 0
	s_addc_u32 s17, s21, 0
	s_mov_b32 s51, -2
	v_mov_b32_e32 v3, v2
	v_mov_b32_e32 v4, v2
	v_mov_b32_e32 v5, v2
	v_mov_b32_e32 v6, v2
	v_mov_b32_e32 v7, v2
	v_mov_b32_e32 v8, v2
	v_mov_b32_e32 v9, v2
	v_mov_b32_e32 v18, v2
	v_mov_b32_e32 v19, v2
	v_mov_b32_e32 v20, v2
	v_mov_b32_e32 v21, v2
	v_mov_b32_e32 v22, v2
	v_mov_b32_e32 v23, v2
	v_mov_b32_e32 v24, v2
	v_mov_b32_e32 v25, v2
	v_mov_b32_e32 v34, v2
	v_mov_b32_e32 v35, v2
	v_mov_b32_e32 v36, v2
	v_mov_b32_e32 v37, v2
	v_mov_b32_e32 v38, v2
	v_mov_b32_e32 v39, v2
	v_mov_b32_e32 v40, v2
	v_mov_b32_e32 v41, v2
	v_mov_b32_e32 v50, v2
	v_mov_b32_e32 v51, v2
	v_mov_b32_e32 v52, v2
	v_mov_b32_e32 v53, v2
	v_mov_b32_e32 v54, v2
	v_mov_b32_e32 v55, v2
	v_mov_b32_e32 v56, v2
	v_mov_b32_e32 v57, v2
	v_mov_b32_e32 v10, v2
	v_mov_b32_e32 v11, v2
	v_mov_b32_e32 v12, v2
	v_mov_b32_e32 v13, v2
	v_mov_b32_e32 v14, v2
	v_mov_b32_e32 v15, v2
	v_mov_b32_e32 v16, v2
	v_mov_b32_e32 v17, v2
	v_mov_b32_e32 v26, v2
	v_mov_b32_e32 v27, v2
	v_mov_b32_e32 v28, v2
	v_mov_b32_e32 v29, v2
	v_mov_b32_e32 v30, v2
	v_mov_b32_e32 v31, v2
	v_mov_b32_e32 v32, v2
	v_mov_b32_e32 v33, v2
	v_mov_b32_e32 v42, v2
	v_mov_b32_e32 v43, v2
	v_mov_b32_e32 v44, v2
	v_mov_b32_e32 v45, v2
	v_mov_b32_e32 v46, v2
	v_mov_b32_e32 v47, v2
	v_mov_b32_e32 v48, v2
	v_mov_b32_e32 v49, v2
	v_mov_b32_e32 v58, v2
	v_mov_b32_e32 v59, v2
	v_mov_b32_e32 v60, v2
	v_mov_b32_e32 v61, v2
	v_mov_b32_e32 v62, v2
	v_mov_b32_e32 v63, v2
	v_mov_b32_e32 v64, v2
	v_mov_b32_e32 v65, v2
	v_mov_b32_e32 v66, v2
	v_mov_b32_e32 v67, v2
	v_mov_b32_e32 v68, v2
	v_mov_b32_e32 v69, v2
	v_mov_b32_e32 v70, v2
	v_mov_b32_e32 v71, v2
	v_mov_b32_e32 v72, v2
	v_mov_b32_e32 v73, v2
	v_mov_b32_e32 v82, v2
	v_mov_b32_e32 v83, v2
	v_mov_b32_e32 v84, v2
	v_mov_b32_e32 v85, v2
	v_mov_b32_e32 v86, v2
	v_mov_b32_e32 v87, v2
	v_mov_b32_e32 v88, v2
	v_mov_b32_e32 v89, v2
	v_mov_b32_e32 v98, v2
	v_mov_b32_e32 v99, v2
	v_mov_b32_e32 v100, v2
	v_mov_b32_e32 v101, v2
	v_mov_b32_e32 v102, v2
	v_mov_b32_e32 v103, v2
	v_mov_b32_e32 v104, v2
	v_mov_b32_e32 v105, v2
	v_mov_b32_e32 v114, v2
	v_mov_b32_e32 v115, v2
	v_mov_b32_e32 v116, v2
	v_mov_b32_e32 v117, v2
	v_mov_b32_e32 v118, v2
	v_mov_b32_e32 v119, v2
	v_mov_b32_e32 v120, v2
	v_mov_b32_e32 v121, v2
	v_mov_b32_e32 v74, v2
	v_mov_b32_e32 v75, v2
	v_mov_b32_e32 v76, v2
	v_mov_b32_e32 v77, v2
	v_mov_b32_e32 v78, v2
	v_mov_b32_e32 v79, v2
	v_mov_b32_e32 v80, v2
	v_mov_b32_e32 v81, v2
	v_mov_b32_e32 v90, v2
	v_mov_b32_e32 v91, v2
	v_mov_b32_e32 v92, v2
	v_mov_b32_e32 v93, v2
	v_mov_b32_e32 v94, v2
	v_mov_b32_e32 v95, v2
	v_mov_b32_e32 v96, v2
	v_mov_b32_e32 v97, v2
	v_mov_b32_e32 v106, v2
	v_mov_b32_e32 v107, v2
	v_mov_b32_e32 v108, v2
	v_mov_b32_e32 v109, v2
	v_mov_b32_e32 v110, v2
	v_mov_b32_e32 v111, v2
	v_mov_b32_e32 v112, v2
	v_mov_b32_e32 v113, v2
	v_mov_b32_e32 v124, v2
	v_mov_b32_e32 v125, v2
	v_mov_b32_e32 v126, v2
	v_mov_b32_e32 v127, v2
	v_mov_b32_e32 v128, v2
	v_mov_b32_e32 v129, v2
	v_mov_b32_e32 v130, v2
	v_mov_b32_e32 v131, v2
	v_add_u32_e32 v201, 0x80, v0
	v_add_u32_e32 v215, 0x80, v208
	v_add_u32_e32 v217, 0x80, v204
	v_add_u32_e32 v219, 0x80, v206

;     __device__ bool next(int i, Unit& u) const { if (!b.next(i / 3, u)) return false; u.pz = i % 3; return true; }
; #define PG8_BAR __builtin_amdgcn_s_barrier()
; template <class Epi, class Sched>
; __device__ __forceinline__ void gemm_phase(LAS unsigned char* lds, const int tid, const Gemm g, const Sched& S, const Epi& E) {
;     ...
;         const bool has_next = S.next(ui + 1, nxt);
;         const gchar* nA = has_next ? (const gchar*)g.A + (size_t)nxt.pm * tstep + (size_t)nxt.pz * g.zA : cA;
;         const gchar* nB = has_next ? (const gchar*)g.Bt + (size_t)nxt.pn * tstep + (size_t)nxt.pz * g.zB : cB;
;     ...
; #pragma unroll
;         for (int a = 0; a < 2; ++a)
; #pragma unroll
;             for (int b = 0; b < 2; ++b)
; #pragma unroll
;                 for (int m = 0; m < 4; ++m)
; #pragma unroll
;                     for (int n = 0; n < 2; ++n) acc[a][b][m][n] = (f32x4){0.f, 0.f, 0.f, 0.f};
;         cur = nxt; cA = nA; cB = nB; ++ui;
;         if (wr == 1) PG8_BAR;
.LBB0_558:
	s_ashr_i32 s9, s8, 31
	s_lshl_b64 s[16:17], s[8:9], 19
	s_add_u32 s16, s86, s16
	s_addc_u32 s17, s87, s17
	s_and_b64 s[42:43], s[2:3], exec
	s_cselect_b32 s9, s17, s61
	s_cselect_b32 s42, s16, s60
	s_ashr_i32 s7, s6, 31
	s_lshl_b64 s[44:45], s[6:7], 19
	s_add_u32 s56, s15, s44
	s_addc_u32 s57, s23, s45
	s_and_b64 s[44:45], s[2:3], exec
	s_cselect_b32 s7, s57, s21
	s_cselect_b32 s43, s56, s20
	s_add_u32 s44, s20, 0x100
	s_addc_u32 s45, s21, 0
	s_add_u32 s60, s60, 0x40080
	v_mov_b32_e32 v2, 0
	s_addc_u32 s61, s61, 0
	s_mov_b32 s46, -2
	v_mov_b32_e32 v3, v2
	v_mov_b32_e32 v4, v2
	v_mov_b32_e32 v5, v2
	v_mov_b32_e32 v6, v2
	v_mov_b32_e32 v7, v2
	v_mov_b32_e32 v8, v2
	v_mov_b32_e32 v9, v2
	v_mov_b32_e32 v10, v2
	v_mov_b32_e32 v11, v2
	v_mov_b32_e32 v12, v2
	v_mov_b32_e32 v13, v2
	v_mov_b32_e32 v18, v2
	v_mov_b32_e32 v19, v2
	v_mov_b32_e32 v20, v2
	v_mov_b32_e32 v21, v2
	v_mov_b32_e32 v26, v2
	v_mov_b32_e32 v27, v2
	v_mov_b32_e32 v28, v2
	v_mov_b32_e32 v29, v2
	v_mov_b32_e32 v34, v2
	v_mov_b32_e32 v35, v2
	v_mov_b32_e32 v36, v2
	v_mov_b32_e32 v37, v2
	v_mov_b32_e32 v42, v2
	v_mov_b32_e32 v43, v2
	v_mov_b32_e32 v44, v2
	v_mov_b32_e32 v45, v2
	v_mov_b32_e32 v50, v2
	v_mov_b32_e32 v51, v2
	v_mov_b32_e32 v52, v2
	v_mov_b32_e32 v53, v2
	v_mov_b32_e32 v14, v2
	v_mov_b32_e32 v15, v2
	v_mov_b32_e32 v16, v2
	v_mov_b32_e32 v17, v2
	v_mov_b32_e32 v22, v2
	v_mov_b32_e32 v23, v2
	v_mov_b32_e32 v24, v2
	v_mov_b32_e32 v25, v2
	v_mov_b32_e32 v30, v2
	v_mov_b32_e32 v31, v2
	v_mov_b32_e32 v32, v2
	v_mov_b32_e32 v33, v2
	v_mov_b32_e32 v38, v2
	v_mov_b32_e32 v39, v2
	v_mov_b32_e32 v40, v2
	v_mov_b32_e32 v41, v2
	v_mov_b32_e32 v46, v2
	v_mov_b32_e32 v47, v2
	v_mov_b32_e32 v48, v2
	v_mov_b32_e32 v49, v2
	v_mov_b32_e32 v54, v2
	v_mov_b32_e32 v55, v2
	v_mov_b32_e32 v56, v2
	v_mov_b32_e32 v57, v2
	v_mov_b32_e32 v58, v2
	v_mov_b32_e32 v59, v2
	v_mov_b32_e32 v60, v2
	v_mov_b32_e32 v61, v2
	v_mov_b32_e32 v62, v2
	v_mov_b32_e32 v63, v2
	v_mov_b32_e32 v64, v2
	v_mov_b32_e32 v65, v2
	v_mov_b32_e32 v66, v2
	v_mov_b32_e32 v67, v2
	v_mov_b32_e32 v68, v2
	v_mov_b32_e32 v69, v2
	v_mov_b32_e32 v70, v2
	v_mov_b32_e32 v71, v2
	v_mov_b32_e32 v72, v2
	v_mov_b32_e32 v73, v2
	v_mov_b32_e32 v74, v2
	v_mov_b32_e32 v75, v2
	v_mov_b32_e32 v76, v2
	v_mov_b32_e32 v77, v2
	v_mov_b32_e32 v82, v2
	v_mov_b32_e32 v83, v2
	v_mov_b32_e32 v84, v2
	v_mov_b32_e32 v85, v2
	v_mov_b32_e32 v90, v2
	v_mov_b32_e32 v91, v2
	v_mov_b32_e32 v92, v2
	v_mov_b32_e32 v93, v2
	v_mov_b32_e32 v98, v2
	v_mov_b32_e32 v99, v2
	v_mov_b32_e32 v100, v2
	v_mov_b32_e32 v101, v2
	v_mov_b32_e32 v106, v2
	v_mov_b32_e32 v107, v2
	v_mov_b32_e32 v108, v2
	v_mov_b32_e32 v109, v2
	v_mov_b32_e32 v114, v2
	v_mov_b32_e32 v115, v2
	v_mov_b32_e32 v116, v2
	v_mov_b32_e32 v117, v2
	v_mov_b32_e32 v78, v2
	v_mov_b32_e32 v79, v2
	v_mov_b32_e32 v80, v2
	v_mov_b32_e32 v81, v2
	v_mov_b32_e32 v86, v2
	v_mov_b32_e32 v87, v2
	v_mov_b32_e32 v88, v2
	v_mov_b32_e32 v89, v2
	v_mov_b32_e32 v94, v2
	v_mov_b32_e32 v95, v2
	v_mov_b32_e32 v96, v2
	v_mov_b32_e32 v97, v2
	v_mov_b32_e32 v102, v2
	v_mov_b32_e32 v103, v2
	v_mov_b32_e32 v104, v2
	v_mov_b32_e32 v105, v2
	v_mov_b32_e32 v110, v2
	v_mov_b32_e32 v111, v2
	v_mov_b32_e32 v112, v2
	v_mov_b32_e32 v113, v2
	v_mov_b32_e32 v118, v2
	v_mov_b32_e32 v119, v2
	v_mov_b32_e32 v120, v2
	v_mov_b32_e32 v121, v2
	v_mov_b32_e32 v122, v2
	v_mov_b32_e32 v123, v2
	v_mov_b32_e32 v124, v2
	v_mov_b32_e32 v125, v2
	v_mov_b32_e32 v126, v2
	v_mov_b32_e32 v127, v2
	v_mov_b32_e32 v128, v2
	v_mov_b32_e32 v129, v2
	v_add_u32_e32 v161, 0x80, v0
	v_add_u32_e32 v195, 0x80, v134
	v_add_u32_e32 v201, 0x80, v138
	v_add_u32_e32 v227, 0x80, v136

; #define PG8_BAR __builtin_amdgcn_s_barrier()
; template <class Epi, class Sched>
; __device__ __forceinline__ void gemm_phase(LAS unsigned char* lds, const int tid, const Gemm g, const Sched& S, const Epi& E) {
;     ...
; #pragma unroll
;         for (int a = 0; a < 2; ++a)
; #pragma unroll
;             for (int b = 0; b < 2; ++b)
; #pragma unroll
;                 for (int m = 0; m < 4; ++m)
; #pragma unroll
;                     for (int n = 0; n < 2; ++n) acc[a][b][m][n] = (f32x4){0.f, 0.f, 0.f, 0.f};
;         cur = nxt; cA = nA; cB = nB; ++ui;
;         if (wr == 1) PG8_BAR;
.LBB0_597:
	s_add_u32 s31, s20, 0x100
	v_mov_b32_e32 v2, 0
	s_addc_u32 s44, s21, 0
	s_mov_b32 s45, -2
	s_waitcnt lgkmcnt(0)
	v_mov_b32_e32 v3, v2
	v_mov_b32_e32 v4, v2
	v_mov_b32_e32 v5, v2
	v_mov_b32_e32 v6, v2
	v_mov_b32_e32 v7, v2
	v_mov_b32_e32 v8, v2
	v_mov_b32_e32 v9, v2
	v_mov_b32_e32 v18, v2
	v_mov_b32_e32 v19, v2
	v_mov_b32_e32 v20, v2
	v_mov_b32_e32 v21, v2
	v_mov_b32_e32 v22, v2
	v_mov_b32_e32 v23, v2
	v_mov_b32_e32 v24, v2
	v_mov_b32_e32 v25, v2
	v_mov_b32_e32 v34, v2
	v_mov_b32_e32 v35, v2
	v_mov_b32_e32 v36, v2
	v_mov_b32_e32 v37, v2
	v_mov_b32_e32 v38, v2
	v_mov_b32_e32 v39, v2
	v_mov_b32_e32 v40, v2
	v_mov_b32_e32 v41, v2
	v_mov_b32_e32 v50, v2
	v_mov_b32_e32 v51, v2
	v_mov_b32_e32 v52, v2
	v_mov_b32_e32 v53, v2
	v_mov_b32_e32 v54, v2
	v_mov_b32_e32 v55, v2
	v_mov_b32_e32 v56, v2
	v_mov_b32_e32 v57, v2
	v_mov_b32_e32 v10, v2
	v_mov_b32_e32 v11, v2
	v_mov_b32_e32 v12, v2
	v_mov_b32_e32 v13, v2
	v_mov_b32_e32 v14, v2
	v_mov_b32_e32 v15, v2
	v_mov_b32_e32 v16, v2
	v_mov_b32_e32 v17, v2
	v_mov_b32_e32 v26, v2
	v_mov_b32_e32 v27, v2
	v_mov_b32_e32 v28, v2
	v_mov_b32_e32 v29, v2
	v_mov_b32_e32 v30, v2
	v_mov_b32_e32 v31, v2
	v_mov_b32_e32 v32, v2
	v_mov_b32_e32 v33, v2
	v_mov_b32_e32 v42, v2
	v_mov_b32_e32 v43, v2
	v_mov_b32_e32 v44, v2
	v_mov_b32_e32 v45, v2
	v_mov_b32_e32 v46, v2
	v_mov_b32_e32 v47, v2
	v_mov_b32_e32 v48, v2
	v_mov_b32_e32 v49, v2
	v_mov_b32_e32 v58, v2
	v_mov_b32_e32 v59, v2
	v_mov_b32_e32 v60, v2
	v_mov_b32_e32 v61, v2
	v_mov_b32_e32 v62, v2
	v_mov_b32_e32 v63, v2
	v_mov_b32_e32 v64, v2
	v_mov_b32_e32 v65, v2
	v_mov_b32_e32 v66, v2
	v_mov_b32_e32 v67, v2
	v_mov_b32_e32 v68, v2
	v_mov_b32_e32 v69, v2
	v_mov_b32_e32 v70, v2
	v_mov_b32_e32 v71, v2
	v_mov_b32_e32 v72, v2
	v_mov_b32_e32 v73, v2
	v_mov_b32_e32 v82, v2
	v_mov_b32_e32 v83, v2
	v_mov_b32_e32 v84, v2
	v_mov_b32_e32 v85, v2
	v_mov_b32_e32 v86, v2
	v_mov_b32_e32 v87, v2
	v_mov_b32_e32 v88, v2
	v_mov_b32_e32 v89, v2
	v_mov_b32_e32 v98, v2
	v_mov_b32_e32 v99, v2
	v_mov_b32_e32 v100, v2
	v_mov_b32_e32 v101, v2
	v_mov_b32_e32 v102, v2
	v_mov_b32_e32 v103, v2
	v_mov_b32_e32 v104, v2
	v_mov_b32_e32 v105, v2
	v_mov_b32_e32 v114, v2
	v_mov_b32_e32 v115, v2
	v_mov_b32_e32 v116, v2
	v_mov_b32_e32 v117, v2
	v_mov_b32_e32 v118, v2
	v_mov_b32_e32 v119, v2
	v_mov_b32_e32 v120, v2
	v_mov_b32_e32 v121, v2
	v_mov_b32_e32 v74, v2
	v_mov_b32_e32 v75, v2
	v_mov_b32_e32 v76, v2
	v_mov_b32_e32 v77, v2
	v_mov_b32_e32 v78, v2
	v_mov_b32_e32 v79, v2
	v_mov_b32_e32 v80, v2
	v_mov_b32_e32 v81, v2
	v_mov_b32_e32 v90, v2
	v_mov_b32_e32 v91, v2
	v_mov_b32_e32 v92, v2
	v_mov_b32_e32 v93, v2
	v_mov_b32_e32 v94, v2
	v_mov_b32_e32 v95, v2
	v_mov_b32_e32 v96, v2
	v_mov_b32_e32 v97, v2
	v_mov_b32_e32 v106, v2
	v_mov_b32_e32 v107, v2
	v_mov_b32_e32 v108, v2
	v_mov_b32_e32 v109, v2
	v_mov_b32_e32 v110, v2
	v_mov_b32_e32 v111, v2
	v_mov_b32_e32 v112, v2
	v_mov_b32_e32 v113, v2
	v_mov_b32_e32 v122, v2
	v_mov_b32_e32 v123, v2
	v_mov_b32_e32 v124, v2
	v_mov_b32_e32 v125, v2
	v_mov_b32_e32 v126, v2
	v_mov_b32_e32 v127, v2
	v_mov_b32_e32 v128, v2
	v_mov_b32_e32 v129, v2
	v_add_u32_e32 v221, 0x80, v0
	v_add_u32_e32 v223, 0x80, v182
	v_add_u32_e32 v225, 0x80, v178
	v_add_u32_e32 v227, 0x80, v180
